# indexer: key tiles 0/1 staged once per workgroup through two extra ring slots, head-weight loads hoisted, prologue barrier replaces the group-0 barrier
# baseline (speedup 1.0000x reference)
.LBB0_399:
	v_cndmask_b32_e64 v2, v159, v92, s[82:83]
	v_readlane_b32 s74, v252, 26
	v_lshlrev_b32_e32 v88, 1, v2
	v_readlane_b32 s75, v252, 27
	v_or_b32_e32 v2, v88, v95
	s_movk_i32 s80, 0x3400
	v_mov_b64_e32 v[42:43], s[74:75]
	v_readfirstlane_b32 s101, v198
	v_readfirstlane_b32 s100, v88
	s_lshr_b32 s101, s101, 6
	s_lshr_b32 vcc_lo, s100, 12
	s_and_b32 vcc_lo, vcc_lo, 1
	s_mul_i32 vcc_lo, vcc_lo, 0x12000
	v_lshrrev_b32_e32 v75, 1, v93
	v_and_b32_e32 v75, 7, v75
	v_xor_b32_e32 v75, v75, v94
	v_lshlrev_b32_e32 v75, 4, v75
	v_lshl_add_u32 v75, v93, 7, v75
	v_add_u32_e32 v74, vcc_lo, v75
	v_xor_b32_e32 v75, 32, v74
	v_xor_b32_e32 v76, 64, v74
	v_xor_b32_e32 v77, 0x60, v74
	v_lshl_or_b32 v73, v94, 5, v93
	v_lshrrev_b32_e32 v72, 3, v73
	v_mul_u32_u24_e32 v72, 0x3400, v72
	v_lshrrev_b32_e32 v78, 4, v73
	v_and_b32_e32 v73, 7, v73
	v_xor_b32_e32 v73, v73, v78
	v_lshl_add_u32 v72, v73, 4, v72
	v_xor_b32_e32 v73, 64, v72
	v_and_b32_e32 v80, 0x7fe, v88
	v_lshrrev_b32_e32 v80, 5, v80
	v_mov_b32_e32 v79, s101
	v_add_u32_e32 v79, 2, v79
	s_and_b32 s100, s100, 0xf800
	s_mul_i32 s100, s100, 0x3400
	s_add_u32 vcc_hi, s100, 0x3200
	s_lshl_b32 m0, s101, 10
	s_add_u32 m0, m0, vcc_lo
	s_add_u32 m0, m0, 0x10000
	v_mov_b32_e32 v78, s101
	v_and_b32_e32 v78, 1, v78
	v_lshlrev_b32_e32 v78, 6, v78
	v_xor_b32_e32 v78, v78, v72
	s_mul_i32 s100, s101, 0x1a000
	s_add_u32 s100, s100, vcc_hi
	s_add_u32 s100, s74, s100
	s_addc_u32 s101, s75, 0
	s_nop 0
	global_load_lds_dwordx4 v78, s[100:101]
	v_readfirstlane_b32 s101, v79
	s_nop 0
	s_sub_u32 s101, s101, 2
	s_lshl_b32 m0, s101, 12
	s_add_u32 m0, m0, vcc_lo
	s_add_u32 s101, s101, 2
	s_mul_i32 s100, s101, 0x68000
	s_add_u32 s100, s100, vcc_hi
	s_add_u32 s100, s74, s100
	s_addc_u32 s101, s75, 0
	v_cmp_le_u32_e32 vcc, v79, v80
	s_and_b64 vcc, exec, vcc
	s_cbranch_vccz .Lidxd_p
	s_nop 0
	global_load_lds_dwordx4 v72, s[100:101]
	s_add_u32 m0, m0, 0x400
	s_add_u32 s100, s100, 0x1a000
	s_addc_u32 s101, s101, 0
	s_nop 0
	global_load_lds_dwordx4 v73, s[100:101]
	s_add_u32 m0, m0, 0x400
	s_add_u32 s100, s100, 0x1a000
	s_addc_u32 s101, s101, 0
	s_nop 0
	global_load_lds_dwordx4 v72, s[100:101]
	s_add_u32 m0, m0, 0x400
	s_add_u32 s100, s100, 0x1a000
	s_addc_u32 s101, s101, 0
	s_nop 0
	global_load_lds_dwordx4 v73, s[100:101]
	s_add_u32 m0, m0, 0x400
	s_add_u32 s100, s100, 0x1a000
	s_addc_u32 s101, s101, 0
	s_add_u32 m0, m0, 0x7000
	s_add_u32 s100, s100, 0x2d8000
	s_addc_u32 s101, s101, 0
	v_add_u32_e32 v79, 8, v79
	v_cmp_le_u32_e32 vcc, v79, v80
	s_and_b64 vcc, exec, vcc
	s_cbranch_vccz .Lidxd_p
	s_nop 0
	global_load_lds_dwordx4 v72, s[100:101]
	s_add_u32 m0, m0, 0x400
	s_add_u32 s100, s100, 0x1a000
	s_addc_u32 s101, s101, 0
	s_nop 0
	global_load_lds_dwordx4 v73, s[100:101]
	s_add_u32 m0, m0, 0x400
	s_add_u32 s100, s100, 0x1a000
	s_addc_u32 s101, s101, 0
	s_nop 0
	global_load_lds_dwordx4 v72, s[100:101]
	s_add_u32 m0, m0, 0x400
	s_add_u32 s100, s100, 0x1a000
	s_addc_u32 s101, s101, 0
	s_nop 0
	global_load_lds_dwordx4 v73, s[100:101]
	s_add_u32 m0, m0, 0x400
	s_add_u32 s100, s100, 0x1a000
	s_addc_u32 s101, s101, 0
	s_sub_u32 m0, m0, 0x9000
	s_add_u32 s100, s100, 0x2d8000
	s_addc_u32 s101, s101, 0
	v_add_u32_e32 v79, 8, v79
.Lidxd_p:
	v_mad_i64_i32 v[4:5], s[74:75], v2, s80, v[42:43]
	v_lshl_add_u64 v[4:5], v[4:5], 0, v[0:1]
	v_mov_b32_e32 v87, v1
	v_lshl_add_u64 v[4:5], v[4:5], 0, v[86:87]
	s_mov_b64 s[74:75], 0x1200
	v_lshl_add_u64 v[34:35], v[4:5], 0, s[74:75]
	v_add_co_u32_e32 v4, vcc, 0x1000, v4
	global_load_dwordx4 v[10:13], v[34:35], off offset:64
	s_nop 0
	v_addc_co_u32_e32 v5, vcc, 0, v5, vcc
	global_load_dwordx4 v[14:17], v[4:5], off offset:512
	v_ashrrev_i32_e32 v3, 31, v2
	v_lshlrev_b64 v[2:3], 8, v[2:3]
	v_lshl_add_u64 v[44:45], v[82:83], 0, v[2:3]
	global_load_dwordx4 v[18:21], v[44:45], off
	global_load_dwordx4 v[22:25], v[44:45], off offset:16
	global_load_dwordx4 v[26:29], v[44:45], off offset:32
	global_load_dwordx4 v[30:33], v[44:45], off offset:48
	global_load_dwordx4 v[6:9], v[34:35], off offset:32
	global_load_dwordx4 v[2:5], v[34:35], off offset:96
	s_movk_i32 s2, 0xf800
	v_and_b32_e32 v177, 0x7fe, v88
	v_or_b32_e32 v184, v88, v94
	v_mad_i64_i32 v[184:185], vcc, v184, s80, v[42:43]
	v_add_co_u32_e32 v184, vcc, 0x3300, v184
	s_nop 1
	v_addc_co_u32_e32 v185, vcc, 0, v185, vcc
	global_load_dwordx4 v[66:69], v[184:185], off
	global_load_dwordx4 v[180:183], v[184:185], off offset:16
	s_waitcnt vmcnt(7)
	v_lshlrev_b32_e32 v34, 16, v10
	v_and_b32_e32 v10, 0xffff0000, v10
	v_lshlrev_b32_e32 v36, 16, v11
	v_and_b32_e32 v38, 0xffff0000, v11
	v_lshlrev_b32_e32 v40, 16, v12
	v_and_b32_e32 v12, 0xffff0000, v12
	v_lshlrev_b32_e32 v46, 16, v13
	v_and_b32_e32 v48, 0xffff0000, v13
	s_waitcnt vmcnt(6)
	v_lshlrev_b32_e32 v35, 16, v14
	v_and_b32_e32 v11, 0xffff0000, v14
	v_lshlrev_b32_e32 v37, 16, v15
	v_and_b32_e32 v39, 0xffff0000, v15
	v_lshlrev_b32_e32 v41, 16, v16
	v_and_b32_e32 v13, 0xffff0000, v16
	v_lshlrev_b32_e32 v47, 16, v17
	v_and_b32_e32 v49, 0xffff0000, v17
	s_waitcnt vmcnt(5)
	v_pk_mul_f32 v[14:15], v[18:19], v[34:35] op_sel:[0,1] op_sel_hi:[1,0]
	v_pk_mul_f32 v[16:17], v[18:19], v[34:35]
	v_pk_mul_f32 v[18:19], v[20:21], v[10:11] op_sel:[0,1] op_sel_hi:[1,0]
	v_pk_mul_f32 v[10:11], v[20:21], v[10:11]
	s_waitcnt vmcnt(4)
	v_pk_mul_f32 v[20:21], v[22:23], v[36:37] op_sel:[0,1] op_sel_hi:[1,0]
	v_pk_mul_f32 v[22:23], v[22:23], v[36:37]
	v_pk_mul_f32 v[34:35], v[24:25], v[38:39] op_sel:[0,1] op_sel_hi:[1,0]
	v_pk_mul_f32 v[24:25], v[24:25], v[38:39]
	s_waitcnt vmcnt(3)
	v_pk_mul_f32 v[36:37], v[26:27], v[40:41] op_sel:[0,1] op_sel_hi:[1,0]
	v_pk_mul_f32 v[26:27], v[26:27], v[40:41]
	v_pk_mul_f32 v[38:39], v[28:29], v[12:13] op_sel:[0,1] op_sel_hi:[1,0]
	v_pk_mul_f32 v[12:13], v[28:29], v[12:13]
	s_waitcnt vmcnt(2)
	v_pk_mul_f32 v[28:29], v[30:31], v[46:47] op_sel:[0,1] op_sel_hi:[1,0]
	v_pk_mul_f32 v[30:31], v[30:31], v[46:47]
	v_pk_mul_f32 v[40:41], v[32:33], v[48:49] op_sel:[0,1] op_sel_hi:[1,0]
	v_pk_mul_f32 v[32:33], v[32:33], v[48:49]
	v_sub_f32_e32 v14, v14, v15
	v_add_f32_e32 v15, v17, v16
	v_sub_f32_e32 v16, v18, v19
	v_add_f32_e32 v10, v10, v11
	v_sub_f32_e32 v11, v20, v21
	v_add_f32_e32 v17, v22, v23
	v_sub_f32_e32 v18, v34, v35
	v_add_f32_e32 v19, v24, v25
	v_sub_f32_e32 v20, v36, v37
	v_add_f32_e32 v21, v26, v27
	v_sub_f32_e32 v22, v38, v39
	v_add_f32_e32 v12, v12, v13
	v_sub_f32_e32 v13, v28, v29
	v_add_f32_e32 v23, v30, v31
	v_sub_f32_e32 v24, v40, v41
	v_add_f32_e32 v25, v32, v33
	v_cvt_pk_bf16_f32 v38, v14, v16
	v_cvt_pk_bf16_f32 v39, v11, v18
	v_cvt_pk_bf16_f32 v40, v20, v22
	v_cvt_pk_bf16_f32 v41, v13, v24
	v_cvt_pk_bf16_f32 v34, v15, v10
	v_cvt_pk_bf16_f32 v35, v17, v19
	v_cvt_pk_bf16_f32 v36, v21, v12
	v_cvt_pk_bf16_f32 v37, v23, v25
	global_load_dwordx4 v[10:13], v[44:45], off offset:128
	global_load_dwordx4 v[14:17], v[44:45], off offset:144
	global_load_dwordx4 v[18:21], v[44:45], off offset:160
	global_load_dwordx4 v[22:25], v[44:45], off offset:176
	v_or_b32_e32 v26, v88, v94
	v_and_or_b32 v28, v88, s2, v93
	v_mad_i64_i32 v[26:27], s[74:75], v26, s80, v[42:43]
	s_movk_i32 s2, 0x3000
	v_mad_i64_i32 v[28:29], s[74:75], v28, s80, v[42:43]
	v_add_co_u32_e32 v32, vcc, s2, v26
	v_lshl_add_u64 v[30:31], v[28:29], 0, v[86:87]
	s_nop 0
	v_addc_co_u32_e32 v33, vcc, 0, v27, vcc
	s_waitcnt vmcnt(5)
	v_lshlrev_b32_e32 v27, 16, v6
	v_and_b32_e32 v29, 0xffff0000, v6
	v_lshlrev_b32_e32 v43, 16, v7
	v_and_b32_e32 v7, 0xffff0000, v7
	v_lshlrev_b32_e32 v45, 16, v8
	v_and_b32_e32 v47, 0xffff0000, v8
	v_lshlrev_b32_e32 v49, 16, v9
	v_and_b32_e32 v9, 0xffff0000, v9
	s_waitcnt vmcnt(4)
	v_lshlrev_b32_e32 v26, 16, v2
	v_and_b32_e32 v28, 0xffff0000, v2
	v_lshlrev_b32_e32 v42, 16, v3
	v_and_b32_e32 v6, 0xffff0000, v3
	v_lshlrev_b32_e32 v44, 16, v4
	v_and_b32_e32 v46, 0xffff0000, v4
	v_and_b32_e32 v8, 0xffff0000, v5
	s_mov_b64 s[74:75], 0x3200
	v_lshlrev_b32_e32 v48, 16, v5
	v_lshl_add_u64 v[90:91], v[30:31], 0, s[74:75]
	v_add_co_u32_e32 v30, vcc, 0x3000, v30
	v_cmp_lt_u32_e64 s[74:75], 31, v177
	s_nop 0
	v_addc_co_u32_e32 v31, vcc, 0, v31, vcc
	s_waitcnt vmcnt(3)
	v_pk_mul_f32 v[2:3], v[10:11], v[26:27] op_sel:[0,1] op_sel_hi:[1,0]
	v_pk_mul_f32 v[4:5], v[10:11], v[26:27]
	v_pk_mul_f32 v[10:11], v[12:13], v[28:29] op_sel:[0,1] op_sel_hi:[1,0]
	v_pk_mul_f32 v[12:13], v[12:13], v[28:29]
	s_waitcnt vmcnt(2)
	v_pk_mul_f32 v[26:27], v[14:15], v[42:43] op_sel:[0,1] op_sel_hi:[1,0]
	v_pk_mul_f32 v[14:15], v[14:15], v[42:43]
	v_pk_mul_f32 v[28:29], v[16:17], v[6:7] op_sel:[0,1] op_sel_hi:[1,0]
	v_pk_mul_f32 v[6:7], v[16:17], v[6:7]
	s_waitcnt vmcnt(1)
	v_pk_mul_f32 v[16:17], v[18:19], v[44:45] op_sel:[0,1] op_sel_hi:[1,0]
	v_pk_mul_f32 v[18:19], v[18:19], v[44:45]
	v_pk_mul_f32 v[42:43], v[20:21], v[46:47] op_sel:[0,1] op_sel_hi:[1,0]
	v_pk_mul_f32 v[20:21], v[20:21], v[46:47]
	s_waitcnt vmcnt(0)
	v_pk_mul_f32 v[46:47], v[24:25], v[8:9] op_sel:[0,1] op_sel_hi:[1,0]
	v_pk_mul_f32 v[44:45], v[22:23], v[48:49] op_sel:[0,1] op_sel_hi:[1,0]
	v_pk_mul_f32 v[22:23], v[22:23], v[48:49]
	v_pk_mul_f32 v[8:9], v[24:25], v[8:9]
	v_sub_f32_e32 v2, v2, v3
	v_add_f32_e32 v3, v4, v5
	v_sub_f32_e32 v4, v10, v11
	v_add_f32_e32 v5, v12, v13
	v_add_f32_e32 v13, v18, v19
	v_sub_f32_e32 v18, v46, v47
	v_sub_f32_e32 v10, v26, v27
	v_add_f32_e32 v11, v14, v15
	v_sub_f32_e32 v12, v28, v29
	v_add_f32_e32 v6, v6, v7
	v_sub_f32_e32 v7, v16, v17
	v_sub_f32_e32 v14, v42, v43
	v_add_f32_e32 v15, v20, v21
	v_sub_f32_e32 v16, v44, v45
	v_add_f32_e32 v17, v22, v23
	v_add_f32_e32 v8, v8, v9
	v_cvt_pk_bf16_f32 v46, v2, v4
	v_cvt_pk_bf16_f32 v47, v10, v12
	v_cvt_pk_bf16_f32 v48, v7, v14
	v_cvt_pk_bf16_f32 v49, v16, v18
	v_cvt_pk_bf16_f32 v42, v3, v5
	v_cvt_pk_bf16_f32 v43, v11, v6
	v_cvt_pk_bf16_f32 v44, v13, v15
	v_cvt_pk_bf16_f32 v45, v17, v8
	s_waitcnt vmcnt(0)
	s_barrier
	v_add_u32_e32 v78, 0x10000, v74
	ds_read_b128 v[6:9], v78
	ds_read_b128 v[58:61], v78 offset:4096
	v_add_u32_e32 v78, 0x10000, v75
	ds_read_b128 v[26:29], v78
	ds_read_b128 v[54:57], v78 offset:4096
	v_add_u32_e32 v78, 0x10000, v76
	ds_read_b128 v[18:21], v78
	ds_read_b128 v[50:53], v78 offset:4096
	v_add_u32_e32 v78, 0x10000, v77
	ds_read_b128 v[22:25], v78
	ds_read_b128 v[62:65], v78 offset:4096
	v_mov_b64_e32 v[2:3], v[66:67]
	v_mov_b64_e32 v[4:5], v[68:69]
	v_mov_b64_e32 v[10:11], v[180:181]
	v_mov_b64_e32 v[12:13], v[182:183]
	v_lshlrev_b32_e32 v174, 16, v2
	v_lshlrev_b32_e32 v166, 16, v10
	v_and_b32_e32 v173, 0xffff0000, v2
	v_and_b32_e32 v165, 0xffff0000, v10
	v_lshlrev_b32_e32 v172, 16, v3
	v_lshlrev_b32_e32 v164, 16, v11
	v_and_b32_e32 v171, 0xffff0000, v3
	v_and_b32_e32 v163, 0xffff0000, v11
	v_lshlrev_b32_e32 v170, 16, v4
	v_lshlrev_b32_e32 v162, 16, v12
	v_and_b32_e32 v169, 0xffff0000, v4
	v_and_b32_e32 v161, 0xffff0000, v12
	v_lshlrev_b32_e32 v168, 16, v5
	v_lshlrev_b32_e32 v160, 16, v13
	v_and_b32_e32 v167, 0xffff0000, v5
	v_and_b32_e32 v89, 0xffff0000, v13
	s_waitcnt lgkmcnt(0)
	v_mfma_f32_32x32x16_bf16 v[2:17], v[38:41], v[6:9], 0
	v_or_b32_e32 v87, v177, v94
	v_mov_b32_e32 v175, 0
	v_mfma_f32_32x32x16_bf16 v[2:17], v[46:49], v[26:29], v[2:17]
	v_mfma_f32_32x32x16_bf16 v[2:17], v[34:37], v[18:21], v[2:17]
	v_mfma_f32_32x32x16_bf16 v[2:17], v[42:45], v[22:25], v[2:17]
	s_and_saveexec_b64 s[80:81], s[74:75]
	s_cbranch_execz .Lidxp_e1
	s_waitcnt lgkmcnt(0)
	v_mfma_f32_32x32x16_bf16 v[18:33], v[38:41], v[58:61], 0
	v_mfma_f32_32x32x16_bf16 v[18:33], v[46:49], v[54:57], v[18:33]
	v_mfma_f32_32x32x16_bf16 v[18:33], v[34:37], v[50:53], v[18:33]
	v_mfma_f32_32x32x16_bf16 v[18:33], v[42:45], v[62:65], v[18:33]
	ds_read_b128 v[58:61], v74 offset:0
	ds_read_b128 v[54:57], v75 offset:0
	ds_read_b128 v[50:53], v76 offset:0
	ds_read_b128 v[62:65], v77 offset:0
	s_nop 3
	v_max_f32_e32 v2, 0, v2
	v_fma_f32 v2, v174, v2, 0
	v_max_f32_e32 v3, 0, v3
	v_fmac_f32_e32 v2, v173, v3
	v_max_f32_e32 v3, 0, v4
	v_fmac_f32_e32 v2, v172, v3
	v_max_f32_e32 v3, 0, v5
	v_fmac_f32_e32 v2, v171, v3
	v_max_f32_e32 v3, 0, v6
	v_fmac_f32_e32 v2, v170, v3
	v_max_f32_e32 v3, 0, v7
	v_fmac_f32_e32 v2, v169, v3
	v_max_f32_e32 v3, 0, v8
	v_fmac_f32_e32 v2, v168, v3
	v_max_f32_e32 v3, 0, v9
	v_fmac_f32_e32 v2, v167, v3
	v_max_f32_e32 v3, 0, v10
	v_fmac_f32_e32 v2, v166, v3
	v_max_f32_e32 v3, 0, v11
	v_fmac_f32_e32 v2, v165, v3
	v_max_f32_e32 v3, 0, v12
	v_fmac_f32_e32 v2, v164, v3
	v_max_f32_e32 v3, 0, v13
	v_fmac_f32_e32 v2, v163, v3
	v_max_f32_e32 v3, 0, v14
	v_fmac_f32_e32 v2, v162, v3
	v_max_f32_e32 v3, 0, v15
	v_fmac_f32_e32 v2, v161, v3
	v_max_f32_e32 v3, 0, v16
	v_fmac_f32_e32 v2, v160, v3
	v_max_f32_e32 v3, 0, v17
	v_fmac_f32_e32 v2, v89, v3
	v_not_b32_e32 v3, v2
	v_or_b32_e32 v4, 0x80000000, v2
	v_cmp_gt_i32_e32 vcc, 0, v2
	s_nop 1
	v_cndmask_b32_e32 v2, v4, v3, vcc
	v_cmp_le_u32_e32 vcc, v93, v87
	s_nop 1
	v_cndmask_b32_e32 v81, 0, v2, vcc
